# canonicalising v_max x,x folded into the consuming max in the diff-attention row-max head and the stick-breaking softplus (freed VALU slots become s_nop so every wait-state distance is unchanged)
# baseline (speedup 1.0000x reference)
.LBB0_249:
	s_add_i32 s8, s27, -1
	s_lshl_b64 s[0:1], s[84:85], 12
	s_add_u32 s100, s18, s0
	s_addc_u32 s101, s19, s1
	s_mov_b32 m0, s33
	s_nop 0
	global_load_lds_dwordx4 v212, s[100:101]
	s_add_u32 s100, s100, 0x3c00
	s_addc_u32 s101, s101, 0
	global_load_lds_dwordx4 v213, s[100:101] offset:1024
	s_add_u32 s100, s100, 0x3c00
	s_addc_u32 s101, s101, 0
	global_load_lds_dwordx4 v214, s[100:101] offset:2048
	s_add_u32 s100, s100, 0x3c00
	s_addc_u32 s101, s101, 0
	global_load_lds_dwordx4 v215, s[100:101] offset:3072
	s_add_u32 s100, s100, 0x4c00
	s_addc_u32 s101, s101, 0
	s_add_i32 m0, s33, 0x1000
	s_nop 0
	global_load_lds_dwordx4 v212, s[100:101]
	s_add_u32 s100, s100, 0x3c00
	s_addc_u32 s101, s101, 0
	global_load_lds_dwordx4 v213, s[100:101] offset:1024
	s_add_u32 s100, s100, 0x3c00
	s_addc_u32 s101, s101, 0
	global_load_lds_dwordx4 v214, s[100:101] offset:2048
	s_add_u32 s100, s100, 0x3c00
	s_addc_u32 s101, s101, 0
	global_load_lds_dwordx4 v215, s[100:101] offset:3072
	s_lshr_b32 s0, s8, 1
	s_mov_b32 s1, s85
	s_lshl_b64 s[0:1], s[0:1], 18
	s_add_u32 s100, s30, s0
	s_addc_u32 s101, s31, s1
	s_and_b32 s6, s84, 32
	s_lshl_b32 s0, s6, 12
	s_add_u32 s100, s100, s0
	s_addc_u32 s101, s101, 0
	s_add_i32 m0, s33, 0x2000
	s_nop 0
	global_load_lds_dwordx4 v216, s[100:101]
	global_load_lds_dwordx4 v216, s[100:101] offset:1024
	global_load_lds_dwordx4 v216, s[100:101] offset:2048
	global_load_lds_dwordx4 v216, s[100:101] offset:3072
	s_add_u32 s100, s100, 0x1000
	s_addc_u32 s101, s101, 0
	s_add_i32 m0, s33, 0x3000
	s_nop 0
	global_load_lds_dwordx4 v216, s[100:101]
	global_load_lds_dwordx4 v216, s[100:101] offset:1024
	global_load_lds_dwordx4 v216, s[100:101] offset:2048
	global_load_lds_dwordx4 v216, s[100:101] offset:3072
	s_waitcnt vmcnt(0)
	ds_read_b128 v[66:69], v179
	ds_read_b128 v[114:117], v180
	ds_read_b128 v[118:121], v181
	ds_read_b128 v[122:125], v182
	ds_read_b128 v[126:129], v184
	ds_read_b128 v[130:133], v185
	ds_read_b128 v[134:137], v186
	ds_read_b128 v[138:141], v187
	s_waitcnt lgkmcnt(7)
	v_mfma_f32_32x32x16_bf16 v[66:81], v[66:69], v[82:85], 0
	s_waitcnt lgkmcnt(6)
	v_mfma_f32_32x32x16_bf16 v[66:81], v[114:117], v[86:89], v[66:81]
	s_waitcnt lgkmcnt(5)
	v_mfma_f32_32x32x16_bf16 v[66:81], v[118:121], v[90:93], v[66:81]
	s_waitcnt lgkmcnt(4)
	v_mfma_f32_32x32x16_bf16 v[66:81], v[122:125], v[94:97], v[66:81]
	s_waitcnt lgkmcnt(3)
	v_mfma_f32_32x32x16_bf16 v[66:81], v[126:129], v[98:101], v[66:81]
	s_waitcnt lgkmcnt(2)
	v_mfma_f32_32x32x16_bf16 v[66:81], v[130:133], v[102:105], v[66:81]
	s_waitcnt lgkmcnt(1)
	v_mfma_f32_32x32x16_bf16 v[66:81], v[134:137], v[106:109], v[66:81]
	s_waitcnt lgkmcnt(0)
	v_mfma_f32_32x32x16_bf16 v[66:81], v[138:141], v[110:113], v[66:81]
	ds_read_b128 v[114:117], v189 offset:14336
	ds_read_b128 v[118:121], v188 offset:14336
	ds_read_b128 v[122:125], v189 offset:12288
	ds_read_b128 v[126:129], v188 offset:12288
	ds_read_b128 v[130:133], v189 offset:10240
	ds_read_b128 v[134:137], v188 offset:10240
	ds_read_b128 v[138:141], v189 offset:8192
	ds_read_b128 v[142:145], v188 offset:8192
	s_nop 3
	v_mul_f32_e64 v155, |v66|, s79
	v_mul_f32_e64 v157, |v67|, s79
	v_exp_f32_e32 v155, v155
	v_exp_f32_e32 v157, v157
	s_nop 0
	v_max_f32_e32 v154, 0, v66
	v_add_f32_e32 v155, 1.0, v155
	v_add_f32_e32 v157, 1.0, v157
	v_log_f32_e32 v156, v155
	v_log_f32_e32 v157, v157
	s_nop 0
	v_max_f32_e32 v155, 0, v67
	v_mul_f32_e64 v159, |v69|, s79
	v_pk_fma_f32 v[156:157], v[156:157], s[74:75], v[154:155] op_sel_hi:[1,0,1]
	v_mul_f32_e64 v155, |v68|, s79
	v_exp_f32_e32 v155, v155
	v_exp_f32_e32 v159, v159
	s_nop 0
	v_max_f32_e32 v154, 0, v68
	v_add_f32_e32 v155, 1.0, v155
	v_add_f32_e32 v159, 1.0, v159
	v_log_f32_e32 v158, v155
	v_log_f32_e32 v159, v159
	s_nop 0
	v_max_f32_e32 v155, 0, v69
	v_sub_f32_e64 v162, -v156, v157
	v_pk_fma_f32 v[160:161], v[158:159], s[74:75], v[154:155] op_sel_hi:[1,0,1]
	v_mul_f32_e64 v155, |v70|, s79
	v_mul_f32_e64 v159, |v71|, s79
	v_exp_f32_e32 v155, v155
	v_exp_f32_e32 v159, v159
	v_sub_f32_e32 v154, v162, v160
	v_sub_f32_e32 v162, v154, v161
	v_add_f32_e32 v155, 1.0, v155
	v_add_f32_e32 v159, 1.0, v159
	v_log_f32_e32 v158, v155
	v_log_f32_e32 v159, v159
	s_nop 0
	s_nop 0
	v_max_f32_e32 v154, 0, v70
	v_max_f32_e32 v155, 0, v71
	v_pk_fma_f32 v[164:165], v[158:159], s[74:75], v[154:155] op_sel_hi:[1,0,1]
	v_mul_f32_e64 v155, |v72|, s79
	v_mul_f32_e64 v159, |v73|, s79
	v_exp_f32_e32 v155, v155
	v_exp_f32_e32 v159, v159
	v_sub_f32_e32 v154, v162, v164
	v_sub_f32_e32 v162, v154, v165
	v_add_f32_e32 v155, 1.0, v155
	v_add_f32_e32 v159, 1.0, v159
	v_log_f32_e32 v158, v155
	v_log_f32_e32 v159, v159
	s_nop 0
	s_nop 0
	v_max_f32_e32 v154, 0, v72
	v_max_f32_e32 v155, 0, v73
	v_pk_fma_f32 v[168:169], v[158:159], s[74:75], v[154:155] op_sel_hi:[1,0,1]
	s_nop 0
	v_sub_f32_e32 v191, v73, v169
	s_nop 0
	v_max_f32_e32 v158, 0, v74
	v_mul_f32_e64 v73, |v74|, s79
	v_exp_f32_e32 v73, v73
	v_sub_f32_e32 v154, v162, v168
	v_sub_f32_e32 v155, v154, v169
	s_nop 0
	v_add_f32_e32 v73, 1.0, v73
	v_log_f32_e32 v162, v73
	s_nop 0
	v_max_f32_e32 v159, 0, v75
	v_mul_f32_e64 v73, |v75|, s79
	v_exp_f32_e32 v73, v73
	s_nop 0
	v_add_f32_e32 v73, 1.0, v73
	v_log_f32_e32 v163, v73
	s_nop 0
	v_pk_fma_f32 v[158:159], v[162:163], s[74:75], v[158:159] op_sel_hi:[1,0,1]
	v_max_f32_e32 v162, 0, v76
	v_mul_f32_e64 v154, |v76|, s79
	v_exp_f32_e32 v154, v154
	v_sub_f32_e64 v73, -v158, v159
	v_add_f32_e32 v154, 1.0, v154
	v_log_f32_e32 v166, v154
	s_nop 0
	v_max_f32_e32 v163, 0, v77
	v_mul_f32_e64 v154, |v77|, s79
	v_exp_f32_e32 v154, v154
	s_nop 0
	v_add_f32_e32 v154, 1.0, v154
	v_log_f32_e32 v167, v154
	s_nop 0
	v_pk_fma_f32 v[162:163], v[166:167], s[74:75], v[162:163] op_sel_hi:[1,0,1]
	v_max_f32_e32 v166, 0, v78
	v_mul_f32_e64 v154, |v78|, s79
	v_exp_f32_e32 v154, v154
	v_sub_f32_e32 v73, v73, v162
	v_sub_f32_e32 v73, v73, v163
	v_add_f32_e32 v154, 1.0, v154
	v_log_f32_e32 v170, v154
	s_nop 0
	v_max_f32_e32 v167, 0, v79
	v_mul_f32_e64 v154, |v79|, s79
	v_exp_f32_e32 v154, v154
	s_nop 0
	v_add_f32_e32 v154, 1.0, v154
	v_log_f32_e32 v171, v154
	s_nop 0
	v_pk_fma_f32 v[166:167], v[170:171], s[74:75], v[166:167] op_sel_hi:[1,0,1]
	v_max_f32_e32 v170, 0, v80
	v_mul_f32_e64 v154, |v80|, s79
	v_exp_f32_e32 v154, v154
	v_sub_f32_e32 v73, v73, v166
	v_sub_f32_e32 v73, v73, v167
	v_add_f32_e32 v154, 1.0, v154
	v_log_f32_e32 v172, v154
	s_nop 0
	v_max_f32_e32 v171, 0, v81
	v_mul_f32_e64 v154, |v81|, s79
	v_exp_f32_e32 v154, v154
	s_nop 0
	v_add_f32_e32 v154, 1.0, v154
	v_log_f32_e32 v173, v154
	s_nop 0
	v_pk_fma_f32 v[172:173], v[172:173], s[74:75], v[170:171] op_sel_hi:[1,0,1]
	s_nop 0
	v_sub_f32_e32 v73, v73, v172
	v_sub_f32_e32 v196, v81, v173
	v_sub_f32_e32 v171, v73, v173
	v_mov_b32_e32 v73, v155
	v_mov_b32_e32 v81, v155
	s_nop 1
	v_permlane32_swap_b32_e32 v73, v81
	v_cndmask_b32_e64 v154, v73, v81, s[38:39]
	v_mov_b32_e32 v73, v171
	v_mov_b32_e32 v81, v171
	s_nop 1
	v_permlane32_swap_b32_e32 v73, v81
	v_cndmask_b32_e64 v170, v73, v81, s[38:39]
	v_add_f32_e32 v73, v171, v154
	v_cndmask_b32_e64 v73, v171, v73, s[42:43]
	v_add_f32_e32 v73, v73, v170
	v_add_f32_e32 v73, v190, v73
	v_pk_add_f32 v[192:193], v[72:73], v[168:169] neg_lo:[0,1] neg_hi:[0,1]
	v_pk_mov_b32 v[168:169], v[164:165], v[168:169] op_sel:[1,0]
	v_add_f32_e32 v72, v192, v193
	v_mov_b32_e32 v192, v71
	v_pk_add_f32 v[168:169], v[192:193], v[168:169] neg_lo:[0,1] neg_hi:[0,1]
	v_add_f32_e32 v81, v191, v73
	v_add_f32_e32 v71, v168, v169
	v_mul_f32_e32 v71, 0x3fb8aa3b, v71
	v_exp_f32_e32 v73, v71
	v_mov_b32_e32 v71, v169
	v_pk_add_f32 v[168:169], v[70:71], v[164:165] neg_lo:[0,1] neg_hi:[0,1]
	v_pk_mov_b32 v[164:165], v[160:161], v[164:165] op_sel:[1,0]
	v_add_f32_e32 v70, v168, v169
	v_mov_b32_e32 v168, v69
	v_pk_add_f32 v[164:165], v[168:169], v[164:165] neg_lo:[0,1] neg_hi:[0,1]
	v_mul_f32_e32 v81, 0x3fb8aa3b, v81
	v_add_f32_e32 v69, v164, v165
	v_mul_f32_e32 v69, 0x3fb8aa3b, v69
	v_exp_f32_e32 v71, v69
	v_mov_b32_e32 v69, v165
	v_pk_add_f32 v[164:165], v[68:69], v[160:161] neg_lo:[0,1] neg_hi:[0,1]
	v_pk_mov_b32 v[160:161], v[156:157], v[160:161] op_sel:[1,0]
	v_add_f32_e32 v68, v164, v165
	v_mov_b32_e32 v164, v67
	v_pk_add_f32 v[160:161], v[164:165], v[160:161] neg_lo:[0,1] neg_hi:[0,1]
	v_exp_f32_e32 v191, v81
	v_add_f32_e32 v67, v160, v161
	v_mul_f32_e32 v67, 0x3fb8aa3b, v67
	v_exp_f32_e32 v69, v67
	v_mov_b32_e32 v67, v161
	v_pk_add_f32 v[66:67], v[66:67], v[156:157] neg_lo:[0,1] neg_hi:[0,1]
	v_pk_mov_b32 v[160:161], v[166:167], v[172:173] op_sel:[1,0]
	v_add_f32_e32 v66, v66, v67
	v_mul_f32_e32 v66, 0x3fb8aa3b, v66
	v_exp_f32_e32 v67, v66
	v_cndmask_b32_e64 v66, 0, v170, s[42:43]
	v_add_f32_e32 v81, v190, v66
	v_pk_add_f32 v[156:157], v[80:81], v[172:173] neg_lo:[0,1] neg_hi:[0,1]
	v_add_f32_e32 v66, v196, v81
	v_add_f32_e32 v80, v156, v157
	v_mov_b32_e32 v156, v79
	v_pk_add_f32 v[156:157], v[156:157], v[160:161] neg_lo:[0,1] neg_hi:[0,1]
	v_mul_f32_e32 v72, 0x3fb8aa3b, v72
	v_add_f32_e32 v79, v156, v157
	v_mul_f32_e32 v79, 0x3fb8aa3b, v79
	v_exp_f32_e32 v81, v79
	v_mov_b32_e32 v79, v157
	v_pk_add_f32 v[78:79], v[78:79], v[166:167] neg_lo:[0,1] neg_hi:[0,1]
	v_pk_mov_b32 v[156:157], v[162:163], v[166:167] op_sel:[1,0]
	v_add_f32_e32 v78, v78, v79
	v_mul_f32_e32 v78, 0x3fb8aa3b, v78
	v_exp_f32_e32 v160, v78
	v_mov_b32_e32 v78, v77
	v_pk_add_f32 v[78:79], v[78:79], v[156:157] neg_lo:[0,1] neg_hi:[0,1]
	v_mul_f32_e32 v70, 0x3fb8aa3b, v70
	v_add_f32_e32 v77, v78, v79
	v_mul_f32_e32 v77, 0x3fb8aa3b, v77
	v_exp_f32_e32 v156, v77
	v_mov_b32_e32 v77, v79
	v_pk_add_f32 v[76:77], v[76:77], v[162:163] neg_lo:[0,1] neg_hi:[0,1]
	v_pk_mov_b32 v[78:79], v[158:159], v[162:163] op_sel:[1,0]
	v_add_f32_e32 v76, v76, v77
	v_mul_f32_e32 v76, 0x3fb8aa3b, v76
	v_exp_f32_e32 v157, v76
	v_mov_b32_e32 v76, v75
	v_pk_add_f32 v[76:77], v[76:77], v[78:79] neg_lo:[0,1] neg_hi:[0,1]
	v_mul_f32_e32 v68, 0x3fb8aa3b, v68
	v_add_f32_e32 v75, v76, v77
	v_mul_f32_e32 v75, 0x3fb8aa3b, v75
	v_exp_f32_e32 v72, v72
	v_exp_f32_e32 v70, v70
	v_exp_f32_e32 v68, v68
	v_exp_f32_e32 v161, v75
	v_mov_b32_e32 v75, v77
	v_cvt_pk_bf16_f32 v76, v67, v69
	v_cvt_pk_bf16_f32 v77, v68, v71
	v_cvt_pk_bf16_f32 v78, v70, v73
	v_cvt_pk_bf16_f32 v79, v72, v191
	v_pk_add_f32 v[74:75], v[74:75], v[158:159] neg_lo:[0,1] neg_hi:[0,1]
	s_waitcnt lgkmcnt(0)
	v_mfma_f32_32x32x16_bf16 v[50:65], v[142:145], v[76:79], v[50:65]
	v_add_f32_e32 v74, v74, v75
	v_mul_f32_e32 v74, 0x3fb8aa3b, v74
	v_mul_f32_e32 v66, 0x3fb8aa3b, v66
	v_mul_f32_e32 v80, 0x3fb8aa3b, v80
	v_exp_f32_e32 v158, v74
	v_pk_add_f32 v[74:75], v[154:155], v[170:171]
	v_exp_f32_e32 v66, v66
	v_mfma_f32_32x32x16_bf16 v[34:49], v[134:137], v[76:79], v[34:49]
	v_exp_f32_e32 v80, v80
	v_add_f32_e32 v74, v74, v75
	v_cvt_pk_bf16_f32 v68, v158, v161
	v_cvt_pk_bf16_f32 v69, v157, v156
	v_cvt_pk_bf16_f32 v70, v160, v81
	v_cvt_pk_bf16_f32 v71, v80, v66
	v_add_f32_e32 v190, v190, v74
	v_mfma_f32_32x32x16_bf16 v[18:33], v[126:129], v[76:79], v[18:33]
	v_cmp_gt_f32_e32 vcc, s88, v190
	s_cmp_lg_u64 vcc, exec
	s_cselect_b64 s[0:1], -1, 0
	s_cmp_gt_u32 s27, 1
	s_cselect_b64 s[10:11], -1, 0
	s_and_b64 s[0:1], s[0:1], s[10:11]
	s_sub_i32 s84, s84, 32
	v_mfma_f32_32x32x16_bf16 v[2:17], v[118:121], v[76:79], v[2:17]
	s_and_b64 vcc, exec, s[0:1]
	s_mov_b32 s27, s8
	v_mfma_f32_32x32x16_bf16 v[50:65], v[138:141], v[68:71], v[50:65]
	v_mfma_f32_32x32x16_bf16 v[34:49], v[130:133], v[68:71], v[34:49]
	v_mfma_f32_32x32x16_bf16 v[18:33], v[122:125], v[68:71], v[18:33]
	v_mfma_f32_32x32x16_bf16 v[2:17], v[114:117], v[68:71], v[2:17]
	s_cbranch_vccnz .LBB0_249
	s_branch .LBB0_246

.LBB0_265:
	s_nop 9
	s_nop 1
	v_max_f32_e32 v0, v98, v99
	v_max3_f32 v0, v0, v100, v101
	v_max3_f32 v0, v0, v102, v103
	v_max3_f32 v0, v0, v104, v105
	v_max3_f32 v0, v0, v106, v107
	v_max3_f32 v0, v0, v108, v109
	v_max3_f32 v0, v0, v110, v111
	v_max3_f32 v0, v0, v112, v113
	v_max3_f32 v0, v0, v82, v83
	v_max3_f32 v0, v0, v84, v85
	v_max3_f32 v0, v0, v86, v87
	v_max3_f32 v0, v0, v88, v89
	v_max3_f32 v0, v0, v90, v91
	v_max3_f32 v0, v0, v92, v93
	v_max3_f32 v0, v0, v94, v95
	v_max3_f32 v0, v0, v96, v97
	v_mov_b32_e32 v146, v0
	v_mov_b32_e32 v147, v0
	s_nop 1
	v_permlane32_swap_b32_e32 v146, v147
	v_cndmask_b32_e64 v146, v146, v147, s[38:39]
	s_nop 0
	s_cmp_eq_u32 s9, 3
	s_cselect_b64 s[40:41], -1, 0
	s_cmp_lg_u32 s9, 3
	v_max_f32_e32 v146, v0, v146
	s_cbranch_scc0 .LBB0_272
	v_cmp_lt_f32_e32 vcc, s89, v146
	s_mov_b64 s[44:45], 0
	s_mov_b64 s[0:1], 0
	s_cbranch_vccz .LBB0_268
	v_max_f32_e32 v0, v146, v146
	v_max_f32_e32 v0, 0, v0
	s_mov_b64 s[0:1], -1

.LBB0_278:
	s_nop 9
	s_nop 1
	v_max_f32_e32 v0, v98, v99
	v_max3_f32 v0, v0, v100, v101
	v_max3_f32 v0, v0, v102, v103
	v_max3_f32 v0, v0, v104, v105
	v_max3_f32 v0, v0, v106, v107
	v_max3_f32 v0, v0, v108, v109
	v_max3_f32 v0, v0, v110, v111
	v_max3_f32 v0, v0, v112, v113
	v_max3_f32 v0, v0, v82, v83
	v_max3_f32 v0, v0, v84, v85
	v_max3_f32 v0, v0, v86, v87
	v_max3_f32 v0, v0, v88, v89
	v_max3_f32 v0, v0, v90, v91
	v_max3_f32 v0, v0, v92, v93
	v_max3_f32 v0, v0, v94, v95
	v_max3_f32 v0, v0, v96, v97
	v_mov_b32_e32 v130, v0
	v_mov_b32_e32 v131, v0
	s_nop 1
	v_permlane32_swap_b32_e32 v130, v131
	v_cndmask_b32_e64 v130, v130, v131, s[38:39]
	s_nop 0
	v_max_f32_e32 v0, v0, v130
	v_cmp_lt_f32_e32 vcc, s89, v0
	s_cmp_lg_u64 vcc, 0
	s_cselect_b64 s[0:1], -1, 0
	s_cbranch_vccz .LBB0_280
	v_max_f32_e32 v0, v0, v0
	v_max_f32_e32 v0, 0, v0
	v_pk_add_f32 v[98:99], v[98:99], v[0:1] op_sel_hi:[1,0] neg_lo:[0,1] neg_hi:[0,1]
	v_pk_add_f32 v[82:83], v[82:83], v[0:1] op_sel_hi:[1,0] neg_lo:[0,1] neg_hi:[0,1]
	v_pk_add_f32 v[100:101], v[100:101], v[0:1] op_sel_hi:[1,0] neg_lo:[0,1] neg_hi:[0,1]
	v_pk_add_f32 v[84:85], v[84:85], v[0:1] op_sel_hi:[1,0] neg_lo:[0,1] neg_hi:[0,1]
	v_pk_add_f32 v[102:103], v[102:103], v[0:1] op_sel_hi:[1,0] neg_lo:[0,1] neg_hi:[0,1]
	v_pk_add_f32 v[86:87], v[86:87], v[0:1] op_sel_hi:[1,0] neg_lo:[0,1] neg_hi:[0,1]
	v_pk_add_f32 v[104:105], v[104:105], v[0:1] op_sel_hi:[1,0] neg_lo:[0,1] neg_hi:[0,1]
	v_pk_add_f32 v[88:89], v[88:89], v[0:1] op_sel_hi:[1,0] neg_lo:[0,1] neg_hi:[0,1]
	v_pk_add_f32 v[106:107], v[106:107], v[0:1] op_sel_hi:[1,0] neg_lo:[0,1] neg_hi:[0,1]
	v_pk_add_f32 v[90:91], v[90:91], v[0:1] op_sel_hi:[1,0] neg_lo:[0,1] neg_hi:[0,1]
	v_pk_add_f32 v[108:109], v[108:109], v[0:1] op_sel_hi:[1,0] neg_lo:[0,1] neg_hi:[0,1]
	v_pk_add_f32 v[92:93], v[92:93], v[0:1] op_sel_hi:[1,0] neg_lo:[0,1] neg_hi:[0,1]
	v_pk_add_f32 v[110:111], v[110:111], v[0:1] op_sel_hi:[1,0] neg_lo:[0,1] neg_hi:[0,1]
	v_pk_add_f32 v[94:95], v[94:95], v[0:1] op_sel_hi:[1,0] neg_lo:[0,1] neg_hi:[0,1]
	v_pk_add_f32 v[112:113], v[112:113], v[0:1] op_sel_hi:[1,0] neg_lo:[0,1] neg_hi:[0,1]
	v_pk_add_f32 v[96:97], v[96:97], v[0:1] op_sel_hi:[1,0] neg_lo:[0,1] neg_hi:[0,1]
	v_add_f32_e32 v227, v227, v0
	v_exp_f32_e64 v0, -v0
	v_xor_b32_e32 v66, 0x80000000, v227
	v_mov_b32_e32 v67, v66
	v_mov_b32_e32 v68, v66
	v_mov_b32_e32 v69, v66
	v_mov_b32_e32 v70, v66
	v_mov_b32_e32 v71, v66
	v_mov_b32_e32 v72, v66
	v_mov_b32_e32 v73, v66
	v_mov_b32_e32 v74, v66
	v_mov_b32_e32 v75, v66
	v_mov_b32_e32 v76, v66
	v_mov_b32_e32 v77, v66
	v_mov_b32_e32 v78, v66
	v_mov_b32_e32 v79, v66
	v_mov_b32_e32 v80, v66
	v_mov_b32_e32 v81, v66
	s_branch .LBB0_281
